# mixer-A PV: V fragment LDS reads 4..8 issued with the first three during the softmax (MFMA shadow fill)
# baseline (speedup 1.0000x reference)
.LBB0_488:
	s_waitcnt lgkmcnt(0)
	s_mul_i32 s0, s8, 0x9000
	v_lshlrev_b32_e32 v32, 1, v108
	v_add3_u32 v106, s0, v118, v32
	v_mov_b32_e32 v128, v33
	ds_read_b128 v[32:35], v106 offset:4608
	ds_read_b128 v[36:39], v106
	ds_read_b128 v[130:133], v106 offset:32
	ds_read_b128 v[134:137], v106 offset:4640
	s_waitcnt lgkmcnt(2)
	v_mfma_f32_32x32x16_bf16 v[48:63], v[36:39], v[64:67], 0
	v_cmp_gt_i32_e32 vcc, 0, v126
	s_and_b64 vcc, exec, vcc
	v_mfma_f32_32x32x16_bf16 v[32:47], v[32:35], v[64:67], 0
	s_waitcnt lgkmcnt(1)
	v_mfma_f32_32x32x16_bf16 v[48:63], v[130:133], v[68:71], v[48:63]
	s_waitcnt lgkmcnt(0)
	v_mfma_f32_32x32x16_bf16 v[32:47], v[134:137], v[68:71], v[32:47]
	ds_read_b128 v[130:133], v106 offset:64
	ds_read_b128 v[134:137], v106 offset:4672
	s_waitcnt lgkmcnt(1)
	v_mfma_f32_32x32x16_bf16 v[48:63], v[130:133], v[72:75], v[48:63]
	s_waitcnt lgkmcnt(0)
	v_mfma_f32_32x32x16_bf16 v[32:47], v[134:137], v[72:75], v[32:47]
	ds_read_b128 v[130:133], v106 offset:96
	ds_read_b128 v[134:137], v106 offset:4704
	s_waitcnt lgkmcnt(1)
	v_mfma_f32_32x32x16_bf16 v[48:63], v[130:133], v[76:79], v[48:63]
	s_waitcnt lgkmcnt(0)
	v_mfma_f32_32x32x16_bf16 v[32:47], v[134:137], v[76:79], v[32:47]
	ds_read2_b32 v[146:147], v127 offset0:58 offset1:59
	ds_read2_b32 v[148:149], v127 offset0:2 offset1:3
	ds_read2_b32 v[150:151], v127 offset1:1
	ds_read2_b32 v[152:153], v127 offset0:18 offset1:19
	ds_read2_b32 v[154:155], v127 offset0:16 offset1:17
	ds_read2_b32 v[156:157], v127 offset0:56 offset1:57
	ds_read2_b32 v[158:159], v127 offset0:10 offset1:11
	ds_read2_b32 v[160:161], v127 offset0:8 offset1:9
	ds_read2_b32 v[162:163], v127 offset0:50 offset1:51
	ds_read2_b32 v[164:165], v127 offset0:48 offset1:49
	ds_read2_b32 v[166:167], v127 offset0:42 offset1:43
	ds_read2_b32 v[168:169], v127 offset0:40 offset1:41
	ds_read2_b32 v[170:171], v127 offset0:34 offset1:35
	ds_read2_b32 v[172:173], v127 offset0:32 offset1:33
	ds_read2_b32 v[174:175], v127 offset0:26 offset1:27
	ds_read2_b32 v[176:177], v127 offset0:24 offset1:25
	s_waitcnt lgkmcnt(15)
	v_fmamk_f32 v107, v48, 0x3e38aa3b, v147
	v_fmamk_f32 v106, v49, 0x3e38aa3b, v146
	v_max3_f32 v129, v128, v107, v106
	s_waitcnt lgkmcnt(10)
	v_fmamk_f32 v49, v50, 0x3e38aa3b, v157
	v_fmamk_f32 v48, v51, 0x3e38aa3b, v156
	v_max3_f32 v129, v129, v49, v48
	s_waitcnt lgkmcnt(9)
	v_fmamk_f32 v134, v41, 0x3e38aa3b, v158
	s_waitcnt lgkmcnt(8)
	v_fmamk_f32 v136, v43, 0x3e38aa3b, v160
	v_fmamk_f32 v138, v45, 0x3e38aa3b, v148
	s_waitcnt lgkmcnt(7)
	v_fmamk_f32 v51, v52, 0x3e38aa3b, v163
	v_fmamk_f32 v50, v53, 0x3e38aa3b, v162
	v_max3_f32 v129, v129, v51, v50
	v_fmamk_f32 v130, v37, 0x3e38aa3b, v152
	v_fmamk_f32 v132, v39, 0x3e38aa3b, v154
	v_fmamk_f32 v140, v47, 0x3e38aa3b, v150
	s_waitcnt lgkmcnt(6)
	v_fmamk_f32 v53, v54, 0x3e38aa3b, v165
	v_fmamk_f32 v52, v55, 0x3e38aa3b, v164
	v_max3_f32 v129, v129, v53, v52
	s_waitcnt lgkmcnt(5)
	v_fmamk_f32 v55, v56, 0x3e38aa3b, v167
	v_fmamk_f32 v54, v57, 0x3e38aa3b, v166
	v_max3_f32 v129, v129, v55, v54
	s_waitcnt lgkmcnt(4)
	v_fmamk_f32 v57, v58, 0x3e38aa3b, v169
	v_fmamk_f32 v56, v59, 0x3e38aa3b, v168
	v_max3_f32 v129, v129, v57, v56
	s_waitcnt lgkmcnt(3)
	v_fmamk_f32 v59, v60, 0x3e38aa3b, v171
	v_fmamk_f32 v58, v61, 0x3e38aa3b, v170
	v_max3_f32 v129, v129, v59, v58
	s_waitcnt lgkmcnt(2)
	v_fmamk_f32 v61, v62, 0x3e38aa3b, v173
	v_fmamk_f32 v60, v63, 0x3e38aa3b, v172
	v_max3_f32 v129, v129, v61, v60
	s_waitcnt lgkmcnt(1)
	v_fmamk_f32 v63, v32, 0x3e38aa3b, v175
	v_fmamk_f32 v62, v33, 0x3e38aa3b, v174
	v_max3_f32 v129, v129, v63, v62
	s_waitcnt lgkmcnt(0)
	v_fmamk_f32 v142, v34, 0x3e38aa3b, v177
	v_fmamk_f32 v32, v35, 0x3e38aa3b, v176
	v_max3_f32 v33, v129, v142, v32
	v_fmamk_f32 v129, v36, 0x3e38aa3b, v153
	v_max3_f32 v33, v33, v129, v130
	v_fmamk_f32 v131, v38, 0x3e38aa3b, v155
	v_max3_f32 v33, v33, v131, v132
	v_fmamk_f32 v133, v40, 0x3e38aa3b, v159
	v_max3_f32 v33, v33, v133, v134
	v_fmamk_f32 v135, v42, 0x3e38aa3b, v161
	v_max3_f32 v33, v33, v135, v136
	v_fmamk_f32 v137, v44, 0x3e38aa3b, v149
	v_max3_f32 v33, v33, v137, v138
	v_fmamk_f32 v139, v46, 0x3e38aa3b, v151
	v_max3_f32 v33, v33, v139, v140
	ds_bpermute_b32 v34, v119, v33
	s_waitcnt lgkmcnt(0)
	v_max_f32_e32 v34, v34, v34
	v_max_f32_e32 v33, v33, v34
	v_sub_f32_e32 v32, v32, v33
	v_sub_f32_e32 v40, v53, v33
	v_exp_f32_e32 v53, v32
	v_sub_f32_e32 v32, v129, v33
	v_sub_f32_e32 v43, v54, v33
	v_exp_f32_e32 v54, v32
	v_sub_f32_e32 v32, v130, v33
	v_sub_f32_e32 v42, v55, v33
	v_exp_f32_e32 v55, v32
	v_sub_f32_e32 v32, v131, v33
	v_sub_f32_e32 v45, v56, v33
	v_exp_f32_e32 v56, v32
	v_sub_f32_e32 v32, v132, v33
	v_sub_f32_e32 v44, v57, v33
	v_exp_f32_e32 v57, v32
	v_sub_f32_e32 v32, v133, v33
	v_sub_f32_e32 v47, v58, v33
	v_exp_f32_e32 v58, v32
	v_sub_f32_e32 v32, v134, v33
	v_sub_f32_e32 v46, v59, v33
	v_exp_f32_e32 v59, v32
	v_sub_f32_e32 v32, v135, v33
	v_sub_f32_e32 v36, v49, v33
	v_sub_f32_e32 v49, v60, v33
	v_exp_f32_e32 v60, v32
	v_sub_f32_e32 v32, v136, v33
	v_sub_f32_e32 v37, v48, v33
	v_sub_f32_e32 v48, v61, v33
	v_exp_f32_e32 v61, v32
	v_sub_f32_e32 v32, v137, v33
	v_sub_f32_e32 v38, v51, v33
	v_sub_f32_e32 v51, v62, v33
	v_exp_f32_e32 v62, v32
	v_sub_f32_e32 v32, v138, v33
	v_sub_f32_e32 v39, v50, v33
	v_sub_f32_e32 v50, v63, v33
	v_exp_f32_e32 v63, v32
	v_sub_f32_e32 v32, v139, v33
	v_sub_f32_e32 v35, v106, v33
	v_exp_f32_e32 v106, v32
	v_sub_f32_e32 v32, v140, v33
	v_add3_u32 v140, s0, v120, v121
	v_add_u32_e32 v144, 0x3000, v140
	v_add_u32_e32 v145, 0x4000, v140
	v_sub_f32_e32 v41, v52, v33
	v_sub_f32_e32 v52, v142, v33
	ds_read2_b64 v[132:135], v144 offset0:128 offset1:130
	ds_read2_b64 v[136:139], v144 offset0:132 offset1:134
	ds_read2_b64 v[140:143], v145 offset0:160 offset1:162
	ds_read2_b64 v[198:201], v145 offset0:164 offset1:166
	ds_read2_b64 v[202:205], v144 offset0:136 offset1:138
	ds_read2_b64 v[206:209], v145 offset0:168 offset1:170
	ds_read2_b64 v[210:213], v144 offset0:140 offset1:142
	ds_read2_b64 v[214:217], v145 offset0:172 offset1:174
	v_sub_f32_e32 v128, v128, v33
	v_sub_f32_e32 v34, v107, v33
	v_exp_f32_e32 v34, v34
	v_exp_f32_e32 v35, v35
	v_exp_f32_e32 v36, v36
	v_exp_f32_e32 v37, v37
	v_exp_f32_e32 v38, v38
	v_exp_f32_e32 v39, v39
	v_exp_f32_e32 v40, v40
	v_exp_f32_e32 v41, v41
	v_exp_f32_e32 v107, v32
	v_exp_f32_e32 v32, v128
	v_cvt_pk_bf16_f32 v128, v34, v35
	v_cvt_pk_bf16_f32 v129, v36, v37
	v_cvt_pk_bf16_f32 v130, v38, v39
	v_pk_mul_f32 v[30:31], v[30:31], v[32:33] op_sel_hi:[1,0]
	v_pk_mul_f32 v[28:29], v[28:29], v[32:33] op_sel_hi:[1,0]
	v_pk_mul_f32 v[26:27], v[26:27], v[32:33] op_sel_hi:[1,0]
	v_pk_mul_f32 v[24:25], v[24:25], v[32:33] op_sel_hi:[1,0]
	v_pk_mul_f32 v[22:23], v[22:23], v[32:33] op_sel_hi:[1,0]
	v_pk_mul_f32 v[20:21], v[20:21], v[32:33] op_sel_hi:[1,0]
	v_pk_mul_f32 v[18:19], v[18:19], v[32:33] op_sel_hi:[1,0]
	v_pk_mul_f32 v[16:17], v[16:17], v[32:33] op_sel_hi:[1,0]
	v_cvt_pk_bf16_f32 v131, v40, v41
	v_pk_mul_f32 v[14:15], v[14:15], v[32:33] op_sel_hi:[1,0]
	v_pk_mul_f32 v[12:13], v[12:13], v[32:33] op_sel_hi:[1,0]
	v_pk_mul_f32 v[10:11], v[10:11], v[32:33] op_sel_hi:[1,0]
	v_pk_mul_f32 v[8:9], v[8:9], v[32:33] op_sel_hi:[1,0]
	v_pk_mul_f32 v[6:7], v[6:7], v[32:33] op_sel_hi:[1,0]
	v_pk_mul_f32 v[4:5], v[4:5], v[32:33] op_sel_hi:[1,0]
	v_pk_mul_f32 v[2:3], v[2:3], v[32:33] op_sel_hi:[1,0]
	v_pk_mul_f32 v[0:1], v[0:1], v[32:33] op_sel_hi:[1,0]
	s_waitcnt lgkmcnt(7)
	v_mfma_f32_32x32x16_bf16 v[16:31], v[132:135], v[128:131], v[16:31]
	v_exp_f32_e32 v42, v42
	v_exp_f32_e32 v43, v43
	v_exp_f32_e32 v44, v44
	v_exp_f32_e32 v45, v45
	v_exp_f32_e32 v46, v46
	v_exp_f32_e32 v47, v47
	s_waitcnt lgkmcnt(5)
	v_mfma_f32_32x32x16_bf16 v[0:15], v[140:143], v[128:131], v[0:15]
	v_exp_f32_e32 v48, v48
	v_exp_f32_e32 v49, v49
	v_cvt_pk_bf16_f32 v128, v42, v43
	v_cvt_pk_bf16_f32 v129, v44, v45
	v_cvt_pk_bf16_f32 v130, v46, v47
	v_cvt_pk_bf16_f32 v131, v48, v49
	v_exp_f32_e32 v50, v50
	v_exp_f32_e32 v51, v51
	v_mfma_f32_32x32x16_bf16 v[16:31], v[136:139], v[128:131], v[16:31]
	v_exp_f32_e32 v52, v52
	s_waitcnt lgkmcnt(4)
	v_mfma_f32_32x32x16_bf16 v[0:15], v[198:201], v[128:131], v[0:15]
	v_cvt_pk_bf16_f32 v128, v50, v51
	v_cvt_pk_bf16_f32 v129, v52, v53
	v_cvt_pk_bf16_f32 v130, v54, v55
	v_cvt_pk_bf16_f32 v131, v56, v57
	s_nop 0
	s_nop 0
	s_waitcnt lgkmcnt(3)
	v_mfma_f32_32x32x16_bf16 v[16:31], v[202:205], v[128:131], v[16:31]
	s_waitcnt lgkmcnt(2)
	v_mfma_f32_32x32x16_bf16 v[0:15], v[206:209], v[128:131], v[0:15]
	v_cvt_pk_bf16_f32 v128, v58, v59
	v_cvt_pk_bf16_f32 v129, v60, v61
	v_cvt_pk_bf16_f32 v130, v62, v63
	v_cvt_pk_bf16_f32 v131, v106, v107
	s_nop 0
	s_nop 0
	s_waitcnt lgkmcnt(1)
	v_mfma_f32_32x32x16_bf16 v[16:31], v[210:213], v[128:131], v[16:31]
	s_waitcnt lgkmcnt(0)
	v_mfma_f32_32x32x16_bf16 v[0:15], v[214:217], v[128:131], v[0:15]
	s_cbranch_vccnz .LBB0_492
	s_xor_b32 s8, s8, 1
	s_mul_i32 s0, s8, 0x9000
	v_add3_u32 v129, s0, v114, v115
	v_lshlrev_b32_e32 v128, 2, v113
	s_waitcnt vmcnt(0)
	ds_write_b128 v129, v[80:83]
	v_add3_u32 v129, s0, v116, v117
	ds_write_b128 v129, v[84:87]
	v_add3_u32 v128, s0, v128, v112
	s_mov_b32 s1, 0x5040100
	s_mov_b32 s0, 0x7060302
	v_perm_b32 v129, v92, v88, s1
	v_perm_b32 v130, v92, v88, s0
	v_add_u32_e32 v128, 0x3400, v128
	ds_write2_b32 v128, v129, v130 offset1:34
	v_perm_b32 v129, v93, v89, s1
	v_perm_b32 v130, v93, v89, s0
	ds_write2_b32 v128, v129, v130 offset0:68 offset1:102
	v_perm_b32 v129, v94, v90, s1
	v_perm_b32 v130, v94, v90, s0
	ds_write2_b32 v128, v129, v130 offset0:136 offset1:170
	v_subrev_co_u32_e32 v126, vcc, 1, v126
	v_perm_b32 v129, v95, v91, s1
	v_perm_b32 v130, v95, v91, s0
	s_and_b64 vcc, exec, vcc
	ds_write2_b32 v128, v129, v130 offset0:204 offset1:238
	s_cbranch_vccnz .LBB0_491
	v_add_u32_e32 v90, 1, v123
	v_mad_i64_i32 v[80:81], s[0:1], v125, s17, v[102:103]
	v_mad_i64_i32 v[84:85], s[0:1], v124, s17, v[104:105]
	v_mad_u64_u32 v[88:89], s[0:1], v123, s17, v[100:101]
	v_mad_u64_u32 v[92:93], s[0:1], v90, s17, v[100:101]
	global_load_dwordx4 v[80:83], v[80:81], off offset:512
	s_nop 0
	global_load_dwordx4 v[84:87], v[84:85], off offset:512
	s_nop 0
	global_load_dwordx4 v[88:91], v[88:89], off offset:1024
	s_nop 0
	global_load_dwordx4 v[92:95], v[92:93], off offset:1024
